# norm-phase transpose item: non-temporal hint on its 16 streamed f32 x loads
# speedup vs baseline: 1.0165x; 1.0165x over previous
.LBB0_101:
	s_cmpk_gt_i32 s19, 0x30f
	s_mov_b64 s[0:1], -1
	s_cbranch_scc0 .LBB0_175
	s_cmpk_gt_u32 s19, 0x39f
	s_cbranch_scc0 .LBB0_140
	s_cmpk_gt_u32 s19, 0x3df
	s_cbranch_scc0 .LBB0_105
	v_mov_b32_e32 v22, v193
	s_add_i32 s0, s17, 0xffffff00
	s_and_b32 s0, s0, 0x3c0
	s_and_b32 s1, s18, 0x3c0
	v_ashrrev_i32_e32 v23, 6, v22
	s_lshl_b32 s20, s1, 2
	v_add_u32_e32 v4, s0, v23
	s_add_u32 s20, s2, s20
	v_lshlrev_b32_e32 v0, 2, v22
	v_add_u32_e32 v8, 4, v4
	v_add_u32_e32 v10, 8, v4
	v_add_u32_e32 v12, 12, v4
	v_add_u32_e32 v14, 16, v4
	v_add_u32_e32 v16, 20, v4
	v_add_u32_e32 v18, 24, v4
	v_add_u32_e32 v20, 28, v4
	s_addc_u32 s21, s3, 0
	v_and_b32_e32 v0, 0xfc, v0
	v_ashrrev_i32_e32 v5, 31, v4
	v_ashrrev_i32_e32 v9, 31, v8
	v_ashrrev_i32_e32 v11, 31, v10
	v_ashrrev_i32_e32 v13, 31, v12
	v_ashrrev_i32_e32 v15, 31, v14
	v_ashrrev_i32_e32 v17, 31, v16
	v_ashrrev_i32_e32 v19, 31, v18
	v_ashrrev_i32_e32 v21, 31, v20
	v_lshl_add_u64 v[2:3], s[20:21], 0, v[0:1]
	v_lshlrev_b64 v[6:7], 12, v[4:5]
	v_lshlrev_b64 v[8:9], 12, v[8:9]
	v_lshlrev_b64 v[10:11], 12, v[10:11]
	v_lshlrev_b64 v[12:13], 12, v[12:13]
	v_lshlrev_b64 v[14:15], 12, v[14:15]
	v_lshlrev_b64 v[16:17], 12, v[16:17]
	v_lshlrev_b64 v[18:19], 12, v[18:19]
	v_lshlrev_b64 v[20:21], 12, v[20:21]
	v_lshl_add_u64 v[6:7], v[2:3], 0, v[6:7]
	v_lshl_add_u64 v[8:9], v[2:3], 0, v[8:9]
	v_lshl_add_u64 v[10:11], v[2:3], 0, v[10:11]
	v_lshl_add_u64 v[12:13], v[2:3], 0, v[12:13]
	v_lshl_add_u64 v[14:15], v[2:3], 0, v[14:15]
	v_lshl_add_u64 v[16:17], v[2:3], 0, v[16:17]
	v_lshl_add_u64 v[18:19], v[2:3], 0, v[18:19]
	v_lshl_add_u64 v[20:21], v[2:3], 0, v[20:21]
	s_barrier
	global_load_dword v24, v[6:7], off nt
	global_load_dword v25, v[8:9], off nt
	global_load_dword v26, v[10:11], off nt
	global_load_dword v27, v[12:13], off nt
	global_load_dword v28, v[14:15], off nt
	global_load_dword v29, v[16:17], off nt
	global_load_dword v30, v[18:19], off nt
	s_nop 0
	global_load_dword v20, v[20:21], off nt
	v_add_u32_e32 v6, 32, v4
	v_add_u32_e32 v8, 36, v4
	v_add_u32_e32 v10, 40, v4
	v_add_u32_e32 v12, 44, v4
	v_add_u32_e32 v14, 48, v4
	v_add_u32_e32 v16, 52, v4
	v_add_u32_e32 v18, 56, v4
	v_add_u32_e32 v4, 60, v4
	v_ashrrev_i32_e32 v7, 31, v6
	v_ashrrev_i32_e32 v9, 31, v8
	v_ashrrev_i32_e32 v11, 31, v10
	v_ashrrev_i32_e32 v13, 31, v12
	v_ashrrev_i32_e32 v15, 31, v14
	v_ashrrev_i32_e32 v17, 31, v16
	v_ashrrev_i32_e32 v19, 31, v18
	v_ashrrev_i32_e32 v5, 31, v4
	v_lshlrev_b64 v[6:7], 12, v[6:7]
	v_lshlrev_b64 v[8:9], 12, v[8:9]
	v_lshlrev_b64 v[10:11], 12, v[10:11]
	v_lshlrev_b64 v[12:13], 12, v[12:13]
	v_lshlrev_b64 v[14:15], 12, v[14:15]
	v_lshlrev_b64 v[16:17], 12, v[16:17]
	v_lshlrev_b64 v[18:19], 12, v[18:19]
	v_lshlrev_b64 v[4:5], 12, v[4:5]
	v_lshl_add_u64 v[6:7], v[2:3], 0, v[6:7]
	v_lshl_add_u64 v[8:9], v[2:3], 0, v[8:9]
	v_lshl_add_u64 v[10:11], v[2:3], 0, v[10:11]
	v_lshl_add_u64 v[12:13], v[2:3], 0, v[12:13]
	v_lshl_add_u64 v[14:15], v[2:3], 0, v[14:15]
	v_lshl_add_u64 v[16:17], v[2:3], 0, v[16:17]
	v_lshl_add_u64 v[18:19], v[2:3], 0, v[18:19]
	v_lshl_add_u64 v[2:3], v[2:3], 0, v[4:5]
	global_load_dword v4, v[6:7], off nt
	global_load_dword v5, v[8:9], off nt
	s_nop 0
	global_load_dword v6, v[10:11], off nt
	global_load_dword v7, v[12:13], off nt
	global_load_dword v8, v[14:15], off nt
	global_load_dword v9, v[16:17], off nt
	s_nop 0
	global_load_dword v10, v[18:19], off nt
	s_nop 0
	global_load_dword v2, v[2:3], off nt
	s_movk_i32 s20, 0x104
	v_mul_lo_u32 v3, v23, s20
	v_add3_u32 v0, 0, v0, v3
	v_ashrrev_i32_e32 v18, 2, v22
	v_add_u32_e32 v18, s1, v18
	v_ashrrev_i32_e32 v19, 31, v18
	v_readlane_b32 s20, v252, 23
	v_lshlrev_b64 v[18:19], 11, v[18:19]
	v_readlane_b32 s21, v252, 24
	s_waitcnt vmcnt(0)
	ds_write_b32 v0, v24
	s_waitcnt vmcnt(14)
	ds_write_b32 v0, v25 offset:1040
	s_waitcnt vmcnt(13)
	ds_write_b32 v0, v26 offset:2080
	s_waitcnt vmcnt(12)
	ds_write_b32 v0, v27 offset:3120
	s_waitcnt vmcnt(11)
	ds_write_b32 v0, v28 offset:4160
	s_waitcnt vmcnt(10)
	ds_write_b32 v0, v29 offset:5200
	s_waitcnt vmcnt(9)
	ds_write_b32 v0, v30 offset:6240
	s_waitcnt vmcnt(8)
	ds_write_b32 v0, v20 offset:7280
	s_waitcnt vmcnt(7)
	ds_write_b32 v0, v4 offset:8320
	s_waitcnt vmcnt(6)
	ds_write_b32 v0, v5 offset:9360
	s_waitcnt vmcnt(5)
	ds_write_b32 v0, v6 offset:10400
	s_waitcnt vmcnt(4)
	ds_write_b32 v0, v7 offset:11440
	s_waitcnt vmcnt(3)
	ds_write_b32 v0, v8 offset:12480
	s_waitcnt vmcnt(2)
	ds_write_b32 v0, v9 offset:13520
	s_waitcnt vmcnt(1)
	ds_write_b32 v0, v10 offset:14560
	s_waitcnt vmcnt(0)
	ds_write_b32 v0, v2 offset:15600
	v_lshlrev_b32_e32 v0, 4, v22
	v_and_b32_e32 v0, 48, v0
	v_and_b32_e32 v2, -4, v22
	v_mul_u32_u24_e32 v3, 0x104, v0
	v_add3_u32 v14, 0, v2, v3
	v_add_u32_e32 v8, 0x400, v14
	v_add_u32_e32 v12, 0x800, v14
	v_add_u32_e32 v16, 0xc00, v14
	s_waitcnt lgkmcnt(0)
	s_barrier
	ds_read2_b32 v[2:3], v14 offset1:65
	ds_read2_b32 v[4:5], v14 offset0:130 offset1:195
	ds_read2_b32 v[6:7], v8 offset0:4 offset1:69
	ds_read2_b32 v[8:9], v8 offset0:134 offset1:199
	ds_read2_b32 v[10:11], v12 offset0:8 offset1:73
	ds_read2_b32 v[12:13], v12 offset0:138 offset1:203
	ds_read2_b32 v[14:15], v16 offset0:12 offset1:77
	ds_read2_b32 v[16:17], v16 offset0:142 offset1:207
	v_lshl_add_u64 v[18:19], s[20:21], 0, v[18:19]
	v_readlane_b32 s20, v255, 40
	v_readlane_b32 s21, v255, 41
	s_mov_b32 s1, s21
	s_lshl_b32 s20, s0, 1
	v_writelane_b32 v255, s0, 40
	v_lshl_add_u64 v[18:19], v[18:19], 0, s[20:21]
	s_nop 0
	v_writelane_b32 v255, s1, 41
	s_mov_b64 s[0:1], 0
